# HGRN: static s_setprio 1 for the producer waves (the bottleneck half of each SIMD pair)
# baseline (speedup 1.0000x reference)
.LBB0_144:
	s_barrier
	s_setprio 0

.LBB0_153:
	s_and_b64 vcc, exec, s[0:1]
	s_cbranch_vccz .LBB0_145
	s_setprio 1
	s_lshl_b32 s14, s11, 1
	s_add_u32 s0, s76, s14
	s_addc_u32 s1, s77, 0
	s_add_u32 s11, s60, s14
	s_addc_u32 s12, s61, 0
	s_lshl_b32 s10, s10, 1
	v_add_u32_e32 v0, 0xffffff00, v36
	s_add_u32 s10, s11, s10
	s_waitcnt lgkmcnt(0)
	v_ashrrev_i32_e32 v3, 6, v0
	s_addc_u32 s11, s12, 0
	v_lshlrev_b32_e32 v2, 4, v3
	s_and_b64 s[12:13], s[36:37], exec
	v_sub_u32_e32 v0, 0x1fff, v2
	s_mov_b32 s12, 0x19000000
	v_cndmask_b32_e64 v0, v0, v2, s[36:37]
	s_cselect_b32 s12, s12, 0x1d000000
	v_ashrrev_i32_e32 v1, 31, v0
	s_add_u32 s12, s90, s12
	v_and_b32_e32 v4, 63, v36
	v_lshl_add_u64 v[0:1], v[0:1], 0, s[4:5]
	s_addc_u32 s13, s91, 0
	v_lshlrev_b32_e32 v28, 1, v4
	v_lshlrev_b64 v[0:1], 11, v[0:1]
	s_add_u32 s12, s12, s14
	v_or_b32_e32 v0, v0, v28
	s_addc_u32 s13, s13, 0
	v_lshlrev_b64 v[6:7], 1, v[0:1]
	v_lshl_add_u64 v[8:9], s[12:13], 0, v[6:7]
	v_lshl_add_u64 v[6:7], s[0:1], 0, v[6:7]
	global_load_dword v29, v[8:9], off
	global_load_dword v30, v[6:7], off
	v_cmp_gt_u32_e64 s[38:39], 32, v4
	v_mov_b32_e32 v35, 0
	v_mov_b32_e32 v31, 0
	s_and_saveexec_b64 s[14:15], s[38:39]
	s_cbranch_execz .LBB0_156
	v_lshl_add_u64 v[0:1], v[0:1], 1, s[10:11]
	global_load_dword v31, v[0:1], off
